# v53 (conversion split at 8192 + de-serialised gain loads in both conversion loops) + P0 rmsnorm gain vector hoisted out of the row loop
# baseline (speedup 1.0000x reference)
; DI unsigned pk2(float lo, float hi) { f32x2 v = {lo, hi}; return __builtin_bit_cast(unsigned, __builtin_convertvector(v, bf16x2v)); }
; DI void rms_row(const float* xrow, const float* g, bf16_t* orow, int lane) {
;     f32x4 v[8]; float s = 0.f;
; #pragma unroll
;     for (int j = 0; j < 8; ++j) { v[j] = __builtin_nontemporal_load((const f32x4*)xrow + lane + 64 * j); s += (v[j][0] * v[j][0] + v[j][1] * v[j][1]) + (v[j][2] * v[j][2] + v[j][3] * v[j][3]); }
;     const float rstd = rsqrtf(wave_sum(s) * (1.0f / DM) + EPS);
; #pragma unroll
;     for (int j = 0; j < 8; ++j) { const f32x4 gg = *((const f32x4*)g + lane + 64 * j); u32x2 o; o.x = pk2(v[j][0] * rstd * gg[0], v[j][1] * rstd * gg[1]); o.y = pk2(v[j][2] * rstd * gg[2], v[j][3] * rstd * gg[3]);
; __global__ void __launch_bounds__(512, 2) fwd_kernel(Args a) {
;     ...
;         for (int m = gw; m < MP; m += NGW) {
;             if (m < MR) rms_row(m < LP ? x_p + (size_t)m * DM : x_s + (size_t)(m - LP) * DM, ln1_g, H1 + (size_t)m * DM, lane);
.LBB0_25:
	s_cmpk_gt_i32 s10, 0x20ff
	s_cbranch_scc1 .LBB0_34
	v_mov_b32_e32 v13, 0
	v_lshlrev_b32_e32 v12, 3, v152
	v_lshl_add_u64 v[14:15], s[66:67], 0, v[12:13]
	v_lshlrev_b32_e32 v12, 4, v152
	s_waitcnt lgkmcnt(0)
	v_lshl_add_u64 v[16:17], s[54:55], 0, v[12:13]
	s_mov_b64 s[2:3], 0x1000
	v_lshl_add_u64 v[18:19], v[16:17], 0, s[2:3]
	s_mov_b64 s[2:3], 0x1400
	v_lshl_add_u64 v[20:21], v[16:17], 0, s[2:3]
	s_mov_b64 s[2:3], 0x1800
	v_lshl_add_u64 v[22:23], v[16:17], 0, s[2:3]
	s_mov_b64 s[2:3], 0x1c00
	s_ashr_i32 s11, s10, 31
	v_mbcnt_lo_u32_b32 v0, -1, 0
	v_lshl_add_u64 v[24:25], v[16:17], 0, s[2:3]
	s_ashr_i32 s13, s12, 31
	s_lshl_b64 s[2:3], s[10:11], 13
	v_mbcnt_hi_u32_b32 v27, -1, v0
	s_add_u32 s2, s44, s2
	v_and_b32_e32 v0, 64, v27
	s_addc_u32 s3, s45, s3
	s_lshl_b64 s[4:5], s[12:13], 13
	s_mov_b32 s15, 0
	v_lshlrev_b32_e32 v12, 4, v152
	s_movk_i32 s20, 0x1000
	v_mov_b32_e32 v26, 0x358637bd
	s_mov_b32 s21, 0x800000
	v_add_u32_e32 v28, 64, v0
	v_xor_b32_e32 v29, 1, v27
	v_xor_b32_e32 v30, 2, v27
	v_xor_b32_e32 v31, 4, v27
	v_xor_b32_e32 v32, 8, v27
	v_xor_b32_e32 v33, 16, v27
	v_xor_b32_e32 v34, 32, v27
	global_load_dwordx4 v[200:203], v[16:17], off
	global_load_dwordx4 v[204:207], v[16:17], off offset:1024
	global_load_dwordx4 v[208:211], v[16:17], off offset:2048
	global_load_dwordx4 v[212:215], v[16:17], off offset:3072
	global_load_dwordx4 v[216:219], v[18:19], off
	global_load_dwordx4 v[220:223], v[20:21], off
	global_load_dwordx4 v[224:227], v[22:23], off
	global_load_dwordx4 v[228:231], v[24:25], off
	s_branch .LBB0_29
; DI unsigned pk2(float lo, float hi) { f32x2 v = {lo, hi}; return __builtin_bit_cast(unsigned, __builtin_convertvector(v, bf16x2v)); }
; DI void rms_row(const float* xrow, const float* g, bf16_t* orow, int lane) {
;     f32x4 v[8]; float s = 0.f;
; #pragma unroll
;     for (int j = 0; j < 8; ++j) { v[j] = __builtin_nontemporal_load((const f32x4*)xrow + lane + 64 * j); s += (v[j][0] * v[j][0] + v[j][1] * v[j][1]) + (v[j][2] * v[j][2] + v[j][3] * v[j][3]); }
;     const float rstd = rsqrtf(wave_sum(s) * (1.0f / DM) + EPS);
; #pragma unroll
;     for (int j = 0; j < 8; ++j) { const f32x4 gg = *((const f32x4*)g + lane + 64 * j); u32x2 o; o.x = pk2(v[j][0] * rstd * gg[0], v[j][1] * rstd * gg[1]); o.y = pk2(v[j][2] * rstd * gg[2], v[j][3] * rstd * gg[3]);
;         *((u32x2*)orow + lane + 64 * j) = o; }
; }
.LBB0_27:
	global_load_dwordx4 v[36:39], v12, s[18:19] nt
	global_load_dwordx4 v[8:11], v12, s[18:19] offset:1024 nt
	global_load_dwordx4 v[40:43], v12, s[18:19] offset:2048 nt
	global_load_dwordx4 v[44:47], v12, s[18:19] offset:3072 nt
	v_lshl_add_u64 v[0:1], s[18:19], 0, v[12:13]
	v_add_co_u32_e32 v56, vcc, s20, v0
	s_lshl_b64 s[16:17], s[16:17], 12
	s_nop 0
	v_addc_co_u32_e32 v57, vcc, 0, v1, vcc
	global_load_dwordx4 v[4:7], v[56:57], off nt
	global_load_dwordx4 v[48:51], v[56:57], off offset:1024 nt
	global_load_dwordx4 v[0:3], v[56:57], off offset:3072 nt
	global_load_dwordx4 v[52:55], v[56:57], off offset:2048 nt
	v_cmp_lt_i32_e32 vcc, v29, v28
	s_waitcnt vmcnt(7)
	v_mov_b32_e32 v62, v37
	s_waitcnt vmcnt(6)
	v_mov_b32_e32 v63, v9
	v_mov_b32_e32 v66, v39
	v_mov_b32_e32 v67, v11
	v_mov_b32_e32 v60, v36
	v_mov_b32_e32 v61, v8
	v_mov_b32_e32 v64, v38
	v_mov_b32_e32 v65, v10
	s_waitcnt vmcnt(5)
	v_pk_mul_f32 v[68:69], v[42:43], v[42:43]
	v_pk_mul_f32 v[70:71], v[40:41], v[40:41]
	v_pk_mul_f32 v[62:63], v[62:63], v[62:63]
	v_pk_mul_f32 v[66:67], v[66:67], v[66:67]
	v_pk_mov_b32 v[76:77], v[70:71], v[68:69] op_sel:[1,0]
	v_mov_b32_e32 v71, v69
	v_pk_fma_f32 v[60:61], v[60:61], v[60:61], v[62:63]
	v_pk_fma_f32 v[62:63], v[64:65], v[64:65], v[66:67]
	s_waitcnt vmcnt(4)
	v_mul_f32_e32 v72, v45, v45
	v_mul_f32_e32 v74, v47, v47
	v_pk_add_f32 v[64:65], v[76:77], v[70:71]
	v_pk_add_f32 v[60:61], v[60:61], v[62:63]
	v_pk_fma_f32 v[68:69], v[44:45], v[44:45], v[72:73] op_sel_hi:[1,1,0]
	v_pk_fma_f32 v[72:73], v[46:47], v[46:47], v[74:75] op_sel_hi:[1,1,0]
	s_waitcnt vmcnt(3)
	v_mul_f32_e32 v77, v4, v4
	v_mul_f32_e32 v78, v5, v5
	v_pk_add_f32 v[62:63], v[64:65], v[64:65] op_sel:[0,1] op_sel_hi:[1,0]
	v_pk_add_f32 v[60:61], v[60:61], v[60:61] op_sel:[0,1] op_sel_hi:[1,0]
	v_mul_f32_e32 v69, v6, v6
	v_mul_f32_e32 v73, v7, v7
	s_waitcnt vmcnt(2)
	v_pk_mul_f32 v[66:67], v[50:51], v[50:51]
	v_pk_mul_f32 v[70:71], v[48:49], v[48:49]
	v_mov_b32_e32 v63, v78
	v_mov_b32_e32 v61, v77
	v_pk_mov_b32 v[64:65], v[70:71], v[66:67] op_sel:[1,0]
	v_mov_b32_e32 v71, v67
	v_pk_add_f32 v[68:69], v[68:69], v[72:73]
	v_pk_add_f32 v[60:61], v[60:61], v[62:63]
	s_waitcnt vmcnt(0)
	v_mul_f32_e32 v74, v53, v53
	v_mul_f32_e32 v76, v55, v55
	v_pk_add_f32 v[64:65], v[64:65], v[70:71]
	v_pk_add_f32 v[60:61], v[60:61], v[68:69]
	v_mul_f32_e32 v79, v0, v0
	v_mul_f32_e32 v80, v1, v1
	v_mul_f32_e32 v81, v2, v2
	v_mul_f32_e32 v82, v3, v3
	v_pk_fma_f32 v[66:67], v[52:53], v[52:53], v[74:75] op_sel_hi:[1,1,0]
	v_pk_fma_f32 v[74:75], v[54:55], v[54:55], v[76:77] op_sel_hi:[1,1,0]
	v_pk_add_f32 v[64:65], v[64:65], v[64:65] op_sel:[0,1] op_sel_hi:[1,0]
	v_pk_add_f32 v[60:61], v[60:61], v[60:61] op_sel:[0,1] op_sel_hi:[1,0]
	v_mov_b32_e32 v67, v81
	v_mov_b32_e32 v75, v82
	v_mov_b32_e32 v65, v80
	v_mov_b32_e32 v61, v79
	v_pk_add_f32 v[66:67], v[66:67], v[74:75]
	v_pk_add_f32 v[60:61], v[60:61], v[64:65]
	v_cndmask_b32_e32 v35, v27, v29, vcc
	v_pk_add_f32 v[60:61], v[60:61], v[66:67]
	v_lshlrev_b32_e32 v35, 2, v35
	v_add_f32_e32 v60, v60, v61
	ds_bpermute_b32 v35, v35, v60
	v_cmp_lt_i32_e32 vcc, v30, v28
	s_waitcnt lgkmcnt(0)
	v_add_f32_e32 v35, v60, v35
	v_cndmask_b32_e32 v61, v27, v30, vcc
	v_lshlrev_b32_e32 v61, 2, v61
	ds_bpermute_b32 v60, v61, v35
	v_cmp_lt_i32_e32 vcc, v31, v28
	s_waitcnt lgkmcnt(0)
	v_add_f32_e32 v35, v35, v60
	v_cndmask_b32_e32 v61, v27, v31, vcc
	v_lshlrev_b32_e32 v61, 2, v61
	ds_bpermute_b32 v60, v61, v35
	v_cmp_lt_i32_e32 vcc, v32, v28
	s_waitcnt lgkmcnt(0)
	v_add_f32_e32 v35, v35, v60
	v_cndmask_b32_e32 v61, v27, v32, vcc
	v_lshlrev_b32_e32 v61, 2, v61
	ds_bpermute_b32 v60, v61, v35
	v_cmp_lt_i32_e32 vcc, v33, v28
	s_waitcnt lgkmcnt(0)
	v_add_f32_e32 v35, v35, v60
	v_cndmask_b32_e32 v61, v27, v33, vcc
	v_lshlrev_b32_e32 v61, 2, v61
	ds_bpermute_b32 v60, v61, v35
	v_cmp_lt_i32_e32 vcc, v34, v28
	s_waitcnt lgkmcnt(0)
	v_add_f32_e32 v35, v35, v60
	v_cndmask_b32_e32 v61, v27, v34, vcc
	v_lshlrev_b32_e32 v61, 2, v61
	ds_bpermute_b32 v60, v61, v35
	s_waitcnt lgkmcnt(0)
	v_add_f32_e32 v35, v35, v60
	v_fmamk_f32 v35, v35, 0x3a000000, v26
	v_mul_f32_e32 v60, 0x4b800000, v35
	v_cmp_gt_f32_e32 vcc, s21, v35
	s_nop 1
	v_cndmask_b32_e32 v35, v35, v60, vcc
	v_rsq_f32_e32 v35, v35
	v_lshl_add_u64 v[60:61], v[14:15], 0, s[16:17]
	v_mul_f32_e32 v62, 0x45800000, v35
	v_cndmask_b32_e32 v62, v35, v62, vcc
	v_pk_mul_f32 v[36:37], v[36:37], v[62:63] op_sel_hi:[1,0]
	v_pk_mul_f32 v[38:39], v[38:39], v[62:63] op_sel_hi:[1,0]
	v_pk_mul_f32 v[36:37], v[200:201], v[36:37]
	v_pk_mul_f32 v[38:39], v[202:203], v[38:39]
	v_cvt_pk_bf16_f32 v36, v36, v37
	v_cvt_pk_bf16_f32 v37, v38, v39
	global_store_dwordx2 v[60:61], v[36:37], off
	v_pk_mul_f32 v[8:9], v[8:9], v[62:63] op_sel_hi:[1,0]
	v_pk_mul_f32 v[10:11], v[10:11], v[62:63] op_sel_hi:[1,0]
	v_pk_mul_f32 v[8:9], v[204:205], v[8:9]
	v_pk_mul_f32 v[10:11], v[206:207], v[10:11]
	v_cvt_pk_bf16_f32 v8, v8, v9
	v_cvt_pk_bf16_f32 v9, v10, v11
	global_store_dwordx2 v[60:61], v[8:9], off offset:512
	v_pk_mul_f32 v[40:41], v[40:41], v[62:63] op_sel_hi:[1,0]
	v_pk_mul_f32 v[42:43], v[42:43], v[62:63] op_sel_hi:[1,0]
	v_pk_mul_f32 v[40:41], v[208:209], v[40:41]
	v_pk_mul_f32 v[42:43], v[210:211], v[42:43]
	v_cvt_pk_bf16_f32 v40, v40, v41
	v_cvt_pk_bf16_f32 v41, v42, v43
	global_store_dwordx2 v[60:61], v[40:41], off offset:1024
	v_pk_mul_f32 v[44:45], v[44:45], v[62:63] op_sel_hi:[1,0]
	v_pk_mul_f32 v[46:47], v[46:47], v[62:63] op_sel_hi:[1,0]
	v_pk_mul_f32 v[44:45], v[212:213], v[44:45]
	v_pk_mul_f32 v[46:47], v[214:215], v[46:47]
	v_cvt_pk_bf16_f32 v44, v44, v45
	v_cvt_pk_bf16_f32 v45, v46, v47
	global_store_dwordx2 v[60:61], v[44:45], off offset:1536
	v_pk_mul_f32 v[4:5], v[4:5], v[62:63] op_sel_hi:[1,0]
	v_pk_mul_f32 v[6:7], v[6:7], v[62:63] op_sel_hi:[1,0]
	v_pk_mul_f32 v[4:5], v[216:217], v[4:5]
	v_pk_mul_f32 v[6:7], v[218:219], v[6:7]
	v_cvt_pk_bf16_f32 v4, v4, v5
	v_cvt_pk_bf16_f32 v5, v6, v7
	global_store_dwordx2 v[60:61], v[4:5], off offset:2048
	v_pk_mul_f32 v[48:49], v[48:49], v[62:63] op_sel_hi:[1,0]
	v_pk_mul_f32 v[50:51], v[50:51], v[62:63] op_sel_hi:[1,0]
	v_pk_mul_f32 v[48:49], v[220:221], v[48:49]
	v_pk_mul_f32 v[50:51], v[222:223], v[50:51]
	v_cvt_pk_bf16_f32 v48, v48, v49
	v_cvt_pk_bf16_f32 v49, v50, v51
	global_store_dwordx2 v[60:61], v[48:49], off offset:2560
	v_pk_mul_f32 v[52:53], v[52:53], v[62:63] op_sel_hi:[1,0]
	v_pk_mul_f32 v[54:55], v[54:55], v[62:63] op_sel_hi:[1,0]
	v_pk_mul_f32 v[52:53], v[224:225], v[52:53]
	v_pk_mul_f32 v[54:55], v[226:227], v[54:55]
	v_cvt_pk_bf16_f32 v52, v52, v53
	v_cvt_pk_bf16_f32 v53, v54, v55
	global_store_dwordx2 v[60:61], v[52:53], off offset:3072
	v_pk_mul_f32 v[0:1], v[0:1], v[62:63] op_sel_hi:[1,0]
	v_pk_mul_f32 v[2:3], v[2:3], v[62:63] op_sel_hi:[1,0]
	v_pk_mul_f32 v[0:1], v[228:229], v[0:1]
	v_pk_mul_f32 v[2:3], v[230:231], v[2:3]
	v_cvt_pk_bf16_f32 v0, v0, v1
	v_cvt_pk_bf16_f32 v1, v2, v3
